# v19 without the P2/P5/P12 start staggers, and G1's redundant end-of-unit workgroup barrier removed
# speedup vs baseline: 1.0068x; 1.0068x over previous
; #define LBAR() do { asm volatile("s_waitcnt lgkmcnt(0)" ::: "memory"); __builtin_amdgcn_s_barrier(); asm volatile("" ::: "memory"); } while (0)
; DEV f32x4 mfma16(bf16x8 a, bf16x8 b, f32x4 c) { return __builtin_amdgcn_mfma_f32_16x16x32_bf16(a, b, c, 0, 0, 0); }
; DEV u32x4 pack8v(const f32x4 a, const f32x4 b) { u32x4 w; w.x = cvt_pk_bf16(a[0], a[1]); w.y = cvt_pk_bf16(a[2], a[3]); w.z = cvt_pk_bf16(b[0], b[1]); w.w = cvt_pk_bf16(b[2], b[3]); return w; }
; DEV void g1_phase(const Args& a, unsigned char* lds, int G) {
;     ...
;         const u32x4 qraw = qn, kraw = kn, vraw0 = vn0, vraw1 = vn1;
;         u32x4 gf[4];
; #pragma unroll
;         for (int pt = 0; pt < 4; ++pt) gf[pt] = gfn[pt];
;     ...
;         {
;             const int dir = w >> 2;
; #pragma unroll
;             for (int e = 0; e < 2; ++e) {
;                 const int dvt = (w & 3) * 2 + e;
;                 bf16x8 vf[2];
; #pragma unroll
;                 for (int ks = 0; ks < 2; ++ks) vf[ks] = *(const bf16x8*)(sVT + (dvt * 16 + ln) * QP + ks * 32 + kg * 8);
; #pragma unroll
;                 for (int p = 0; p < 2; ++p) {
;                     f32x4 acc[2];
; #pragma unroll
;                     for (int n = 0; n < 2; ++n) { acc[n] = (f32x4){0.f, 0.f, 0.f, 0.f};
; #pragma unroll
;                         for (int ks = 0; ks < 2; ++ks) { const bf16x8 kf = *(const bf16x8*)(sKhT + (dir * 64 + p * 32 + prow(n, ln)) * QP + ks * 32 + kg * 8); acc[n] = mfma16(kf, vf[ks], acc[n]); } }
;                     *(u32x4*)(KV + (((size_t)u * 2 + dir) * 128 + dvt * 16 + ln) * 64 + p * 32 + kg * 8) = pack8v(acc[0], acc[1]);
;                 }
;             }
;         }
;         LBAR();
.LBB0_1503:
	ds_read_b128 v[14:17], v138
	ds_read_b128 v[18:21], v138 offset:64
	ds_read_b128 v[22:25], v139
	ds_read_b128 v[62:65], v139 offset:64
	ds_read_b128 v[66:69], v139 offset:576
	ds_read_b128 v[74:77], v139 offset:640
	v_lshl_add_u64 v[4:5], v[96:97], 0, v[86:87]
	v_add_co_u32_e32 v4, vcc, s53, v4
	ds_read_b128 v[106:109], v139 offset:5184
	ds_read_b128 v[110:113], v139 offset:5248
	s_waitcnt lgkmcnt(5)
	v_mfma_f32_16x16x32_bf16 v[26:29], v[22:25], v[14:17], 0
	v_addc_co_u32_e32 v5, vcc, 0, v5, vcc
	v_lshl_add_u64 v[92:93], v[92:93], 0, s[76:77]
	s_waitcnt lgkmcnt(3)
	v_mfma_f32_16x16x32_bf16 v[70:73], v[66:69], v[14:17], 0
	v_lshl_add_u64 v[96:97], v[96:97], 0, s[78:79]
	s_add_i32 s51, s51, s3
	s_mov_b32 s58, s54
	v_mfma_f32_16x16x32_bf16 v[26:29], v[62:65], v[18:21], v[26:29]
	ds_read_b128 v[102:105], v139 offset:4672
	s_waitcnt lgkmcnt(3)
	v_mfma_f32_16x16x32_bf16 v[70:73], v[74:77], v[18:21], v[70:73]
	s_nop 4
	v_cvt_pk_bf16_f32 v26, v26, v27
	v_cvt_pk_bf16_f32 v27, v28, v29
	s_nop 0
	v_cvt_pk_bf16_f32 v28, v70, v71
	v_cvt_pk_bf16_f32 v29, v72, v73
	global_store_dwordx4 v[4:5], v[26:29], off
	ds_read_b128 v[26:29], v139 offset:4608
	s_waitcnt lgkmcnt(0)
	v_mfma_f32_16x16x32_bf16 v[70:73], v[26:29], v[14:17], 0
	v_mfma_f32_16x16x32_bf16 v[14:17], v[106:109], v[14:17], 0
	v_mfma_f32_16x16x32_bf16 v[70:73], v[102:105], v[18:21], v[70:73]
	v_mfma_f32_16x16x32_bf16 v[14:17], v[110:113], v[18:21], v[14:17]
	s_nop 6
	v_cvt_pk_bf16_f32 v18, v70, v71
	v_cvt_pk_bf16_f32 v19, v72, v73
	v_cvt_pk_bf16_f32 v20, v14, v15
	v_cvt_pk_bf16_f32 v21, v16, v17
	global_store_dwordx4 v[4:5], v[18:21], off offset:64
	ds_read_b128 v[14:17], v140
	ds_read_b128 v[18:21], v140 offset:64
	s_waitcnt lgkmcnt(1)
	v_mfma_f32_16x16x32_bf16 v[22:25], v[22:25], v[14:17], 0
	v_lshl_add_u64 v[4:5], v[94:95], 0, v[86:87]
	v_add_co_u32_e32 v4, vcc, s53, v4
	s_waitcnt lgkmcnt(0)
	v_mfma_f32_16x16x32_bf16 v[22:25], v[62:65], v[18:21], v[22:25]
	v_addc_co_u32_e32 v5, vcc, 0, v5, vcc
	v_mov_b64_e32 v[72:73], v[32:33]
	v_mfma_f32_16x16x32_bf16 v[62:65], v[66:69], v[14:17], 0
	v_mov_b64_e32 v[68:69], v[40:41]
	s_nop 3
	v_cvt_pk_bf16_f32 v22, v22, v23
	v_cvt_pk_bf16_f32 v23, v24, v25
	v_mfma_f32_16x16x32_bf16 v[62:65], v[74:77], v[18:21], v[62:65]
	v_mov_b64_e32 v[76:77], v[36:37]
	v_lshl_add_u64 v[94:95], v[94:95], 0, s[78:79]
	s_andn2_b64 vcc, exec, s[82:83]
	v_mov_b64_e32 v[74:75], v[34:35]
	v_mov_b64_e32 v[70:71], v[30:31]
	s_nop 2
	v_cvt_pk_bf16_f32 v24, v62, v63
	v_cvt_pk_bf16_f32 v25, v64, v65
	global_store_dwordx4 v[4:5], v[22:25], off offset:2048
	v_mov_b64_e32 v[64:65], v[44:45]
	v_mov_b64_e32 v[66:67], v[38:39]
	v_mfma_f32_16x16x32_bf16 v[22:25], v[26:29], v[14:17], 0
	v_mov_b64_e32 v[26:27], v[46:47]
	v_mov_b64_e32 v[62:63], v[42:43]
	v_mov_b64_e32 v[28:29], v[48:49]
	v_mfma_f32_16x16x32_bf16 v[14:17], v[106:109], v[14:17], 0
	v_mfma_f32_16x16x32_bf16 v[22:25], v[102:105], v[18:21], v[22:25]
	v_mfma_f32_16x16x32_bf16 v[14:17], v[110:113], v[18:21], v[14:17]
	s_nop 6
	v_cvt_pk_bf16_f32 v18, v22, v23
	v_cvt_pk_bf16_f32 v19, v24, v25
	v_cvt_pk_bf16_f32 v20, v14, v15
	v_cvt_pk_bf16_f32 v21, v16, v17
	global_store_dwordx4 v[4:5], v[18:21], off offset:2112
	s_waitcnt lgkmcnt(0)
	v_mov_b64_e32 v[22:23], v[50:51]
	v_mov_b64_e32 v[18:19], v[54:55]
	v_mov_b64_e32 v[14:15], v[58:59]
	v_mov_b64_e32 v[24:25], v[52:53]
	v_mov_b64_e32 v[20:21], v[56:57]
	v_mov_b64_e32 v[16:17], v[60:61]
	s_cbranch_vccz .LBB0_1548
